# stagger: half of the workgroups (blockIdx bit 3) start the multi-tile GEMM phases (W_in, MLP up) 3 us late so the two halves' epilogue store bursts do not collide
# speedup vs baseline: 1.0011x; 1.0011x over previous
.LBB0_402:
	s_or_b64 exec, exec, s[2:3]
	s_bitcmp1_b32 s86, 3
	s_cbranch_scc0 .Lstag0
	s_sleep 96
.Lstag0:
	v_readlane_b32 s2, v255, 2
	v_readlane_b32 s3, v255, 3
	s_mul_i32 s2, s2, 0x3000000
	s_add_u32 s17, s92, s2
	v_readlane_b32 s2, v251, 52
	v_mov_b32_e32 v12, v211
	v_readlane_b32 s3, v251, 53
	s_addc_u32 s18, s93, 0
	s_waitcnt lgkmcnt(0)
	s_barrier
	s_andn2_b64 vcc, exec, s[2:3]
	v_readfirstlane_b32 s6, v12
	s_cbranch_vccnz .LBB0_541
	v_lshlrev_b32_e32 v0, 4, v12
	v_add_u32_e32 v2, 0x2000, v0
	v_ashrrev_i32_e32 v3, 31, v2
	v_lshrrev_b32_e32 v3, 22, v3
	v_add_u32_e32 v3, v2, v3
	v_ashrrev_i32_e32 v10, 10, v3
	v_mul_i32_i24_e32 v3, 0x400, v10
	v_sub_u32_e32 v2, v2, v3
	v_lshrrev_b32_e32 v3, 4, v2
	v_bitop3_b32 v2, v3, v2, 32 bitop3:0x6c
	v_ashrrev_i32_e32 v3, 31, v2
	v_lshrrev_b32_e32 v3, 26, v3
	v_add_u32_e32 v3, v2, v3
	v_lshlrev_b32_e32 v4, 3, v10
	v_ashrrev_i32_e32 v11, 6, v3
	v_and_b32_e32 v4, -16, v4
	v_add_u32_e32 v4, v11, v4
	v_and_b32_e32 v5, 3, v11
	s_mov_b32 s2, 0xfffe0
	v_lshrrev_b32_e32 v6, 2, v4
	v_lshlrev_b32_e32 v7, 1, v4
	v_and_or_b32 v5, v4, s2, v5
	v_and_b32_e32 v6, 4, v6
	v_and_b32_e32 v7, 24, v7
	v_and_b32_e32 v3, 0xc0, v3
	v_or3_b32 v5, v5, v6, v7
	v_sub_u32_e32 v2, v2, v3
	v_mov_b32_e32 v7, 1
	v_lshlrev_b32_e32 v6, 5, v10
	v_ashrrev_i16_sdwa v2, v7, sext(v2) dst_sel:DWORD dst_unused:UNUSED_PAD src0_sel:DWORD src1_sel:BYTE_0
	v_and_b32_e32 v6, 32, v6
	v_bfe_i32 v13, v2, 0, 16
	v_add_lshl_u32 v2, v6, v13, 1
	v_lshl_add_u32 v146, v5, 12, v2
	v_lshl_add_u32 v148, v4, 12, v2
	v_bfe_i32 v2, v12, 27, 1
	v_lshrrev_b32_e32 v2, 22, v2
	v_add_u32_e32 v2, v0, v2
	v_and_b32_e32 v2, 0xfffffc00, v2
	v_sub_u32_e32 v0, v0, v2
	v_lshrrev_b32_e32 v2, 4, v0
	v_ashrrev_i32_e32 v3, 31, v12
	v_bitop3_b32 v0, v2, v0, 32 bitop3:0x6c
	v_lshrrev_b32_e32 v3, 26, v3
	v_ashrrev_i32_e32 v2, 31, v0
	v_add_u32_e32 v3, v12, v3
	v_lshrrev_b32_e32 v2, 26, v2
	v_ashrrev_i32_e32 v15, 6, v3
	v_add_u32_e32 v2, v0, v2
	v_lshlrev_b32_e32 v3, 3, v15
	v_ashrrev_i32_e32 v14, 6, v2
	v_and_b32_e32 v3, -16, v3
	v_add_u32_e32 v3, v14, v3
	v_and_b32_e32 v4, 3, v14
	v_lshrrev_b32_e32 v5, 2, v3
	v_lshlrev_b32_e32 v6, 1, v3
	v_and_b32_e32 v2, 0xc0, v2
	s_ashr_i32 s8, s6, 6
	v_and_or_b32 v4, v3, s2, v4
	v_and_b32_e32 v5, 4, v5
	v_and_b32_e32 v6, 24, v6
	v_sub_u32_e32 v0, v0, v2
	s_ashr_i32 s7, s6, 8
	s_lshl_b32 s19, s8, 10
	v_or3_b32 v4, v4, v5, v6
	v_lshlrev_b32_e32 v5, 5, v15
	v_ashrrev_i16_sdwa v0, v7, sext(v0) dst_sel:DWORD dst_unused:UNUSED_PAD src0_sel:DWORD src1_sel:BYTE_0
	v_readlane_b32 s2, v253, 50
	v_and_b32_e32 v5, 32, v5
	v_bfe_i32 v16, v0, 0, 16
	v_readlane_b32 s3, v253, 51
	s_add_u32 s30, s17, s2
	v_add_lshl_u32 v2, v5, v16, 1
	s_addc_u32 s31, s18, s3
	s_add_i32 s24, s19, 0
	v_lshl_add_u32 v0, v4, 12, v2
	s_add_i32 m0, s24, 0x10000
	s_mov_b64 s[4:5], s[14:15]
	global_load_lds_dwordx4 v0, s[30:31]
	s_add_i32 m0, s24, 0x12000
	s_add_u32 s2, s30, 0x80000
	global_load_lds_dwordx4 v146, s[30:31]
	s_addc_u32 s3, s31, 0
	s_add_i32 m0, s24, 0x14000
	v_lshl_add_u32 v150, v3, 12, v2
	global_load_lds_dwordx4 v0, s[2:3]
	s_add_i32 m0, s24, 0x16000
	v_mov_b32_e32 v147, v1
	global_load_lds_dwordx4 v146, s[2:3]
	v_readlane_b32 s2, v253, 56
	v_readlane_b32 s3, v253, 57
	s_add_u32 s2, s4, s2
	s_addc_u32 s3, s5, s3
	s_add_i32 s56, s24, 0x2000
	s_mov_b32 m0, s24
	s_add_u32 s4, s2, 0x80000
	global_load_lds_dwordx4 v150, s[2:3]
	s_mov_b32 m0, s56
	s_addc_u32 s5, s3, 0
	s_add_i32 s57, s24, 0x4000
	global_load_lds_dwordx4 v148, s[2:3]
	s_mov_b32 m0, s57
	s_add_i32 s58, s24, 0x6000
	global_load_lds_dwordx4 v150, s[4:5]
	s_mov_b32 m0, s58
	v_mov_b32_e32 v151, v1
	global_load_lds_dwordx4 v148, s[4:5]
	v_mov_b32_e32 v149, v1
	s_cmp_eq_u32 s7, 1
	v_lshl_add_u64 v[8:9], s[30:31], 0, v[0:1]
	v_lshl_add_u64 v[6:7], s[30:31], 0, v[146:147]
	v_lshl_add_u64 v[2:3], s[2:3], 0, v[150:151]
	s_cselect_b64 s[4:5], -1, 0
	s_cmp_lg_u32 s7, 1
	v_lshl_add_u64 v[4:5], s[2:3], 0, v[148:149]
	s_cbranch_scc1 .LBB0_405
	s_barrier

.LBB0_1653:
	s_cmp_ge_i32 s17, s94
	s_cselect_b64 s[0:1], -1, 0
	s_and_b64 s[8:9], s[0:1], s[2:3]
	s_andn2_b64 vcc, exec, s[8:9]
	s_cbranch_vccnz .LBB0_1695
	s_bitcmp1_b32 s86, 3
	s_cbranch_scc0 .Lstag6
	s_sleep 96
.Lstag6:
	v_readlane_b32 s0, v253, 40
	s_waitcnt vmcnt(3)
	v_mov_b32_e32 v16, v211
	v_readlane_b32 s1, v253, 41
	s_barrier
	s_and_b64 vcc, exec, s[0:1]
	v_readfirstlane_b32 s30, v16
	s_cbranch_vccz .LBB0_1674
	v_lshlrev_b32_e32 v0, 4, v16
	v_add_u32_e32 v2, 0x2000, v0
	v_ashrrev_i32_e32 v3, 31, v2
	v_lshrrev_b32_e32 v3, 22, v3
	v_add_u32_e32 v3, v2, v3
	v_ashrrev_i32_e32 v10, 10, v3
	v_mul_i32_i24_e32 v3, 0x400, v10
	v_sub_u32_e32 v2, v2, v3
	v_lshrrev_b32_e32 v3, 4, v2
	v_bitop3_b32 v2, v3, v2, 32 bitop3:0x6c
	v_ashrrev_i32_e32 v3, 31, v2
	v_readlane_b32 s0, v255, 2
	v_lshrrev_b32_e32 v3, 26, v3
	v_readlane_b32 s1, v255, 3
	v_add_u32_e32 v3, v2, v3
	v_lshlrev_b32_e32 v4, 3, v10
	s_lshl_b64 s[0:1], s[0:1], 25
	v_readlane_b32 s2, v253, 38
	v_ashrrev_i32_e32 v11, 6, v3
	v_and_b32_e32 v4, -16, v4
	s_add_u32 s17, s2, s0
	v_readlane_b32 s0, v253, 39
	v_add_u32_e32 v4, v11, v4
	s_addc_u32 s18, s0, s1
	v_and_b32_e32 v5, 3, v11
	s_mov_b32 s0, 0xfffe0
	v_lshrrev_b32_e32 v6, 2, v4
	v_lshlrev_b32_e32 v7, 1, v4
	v_and_or_b32 v5, v4, s0, v5
	v_and_b32_e32 v6, 4, v6
	v_and_b32_e32 v7, 24, v7
	v_and_b32_e32 v3, 0xc0, v3
	v_or3_b32 v5, v5, v6, v7
	v_sub_u32_e32 v2, v2, v3
	v_mov_b32_e32 v7, 1
	v_lshlrev_b32_e32 v6, 5, v10
	v_ashrrev_i16_sdwa v2, v7, sext(v2) dst_sel:DWORD dst_unused:UNUSED_PAD src0_sel:DWORD src1_sel:BYTE_0
	v_and_b32_e32 v6, 32, v6
	v_bfe_i32 v12, v2, 0, 16
	v_add_lshl_u32 v2, v6, v12, 1
	v_lshl_add_u32 v138, v5, 12, v2
	v_lshl_add_u32 v140, v4, 12, v2
	v_bfe_i32 v2, v16, 27, 1
	v_lshrrev_b32_e32 v2, 22, v2
	v_add_u32_e32 v2, v0, v2
	v_and_b32_e32 v2, 0xfffffc00, v2
	v_sub_u32_e32 v0, v0, v2
	v_lshrrev_b32_e32 v2, 4, v0
	v_ashrrev_i32_e32 v3, 31, v16
	v_bitop3_b32 v0, v2, v0, 32 bitop3:0x6c
	v_lshrrev_b32_e32 v3, 26, v3
	v_ashrrev_i32_e32 v2, 31, v0
	v_add_u32_e32 v3, v16, v3
	v_lshrrev_b32_e32 v2, 26, v2
	v_ashrrev_i32_e32 v14, 6, v3
	v_add_u32_e32 v2, v0, v2
	v_lshlrev_b32_e32 v3, 3, v14
	v_ashrrev_i32_e32 v13, 6, v2
	v_and_b32_e32 v3, -16, v3
	v_add_u32_e32 v3, v13, v3
	v_and_b32_e32 v4, 3, v13
	v_lshrrev_b32_e32 v5, 2, v3
	v_lshlrev_b32_e32 v6, 1, v3
	v_and_b32_e32 v2, 0xc0, v2
	s_ashr_i32 s31, s30, 6
	v_and_or_b32 v4, v3, s0, v4
	v_and_b32_e32 v5, 4, v5
	v_and_b32_e32 v6, 24, v6
	v_sub_u32_e32 v0, v0, v2
	s_ashr_i32 s36, s30, 8
	s_lshl_b32 s19, s31, 10
	v_or3_b32 v4, v4, v5, v6
	v_lshlrev_b32_e32 v5, 5, v14
	v_ashrrev_i16_sdwa v0, v7, sext(v0) dst_sel:DWORD dst_unused:UNUSED_PAD src0_sel:DWORD src1_sel:BYTE_0
	v_readlane_b32 s0, v254, 3
	v_and_b32_e32 v5, 32, v5
	v_bfe_i32 v15, v0, 0, 16
	v_readlane_b32 s1, v254, 4
	s_add_u32 s46, s17, s0
	v_add_lshl_u32 v2, v5, v15, 1
	s_addc_u32 s47, s18, s1
	s_add_i32 s24, s19, 0
	v_lshl_add_u32 v0, v4, 12, v2
	s_add_i32 m0, s24, 0x10000
	v_lshl_add_u32 v142, v3, 12, v2
	global_load_lds_dwordx4 v0, s[46:47]
	s_add_i32 m0, s24, 0x12000
	s_add_u32 s0, s46, 0x80000
	global_load_lds_dwordx4 v138, s[46:47]
	s_addc_u32 s1, s47, 0
	s_add_i32 m0, s24, 0x14000
	v_mov_b32_e32 v139, v1
	global_load_lds_dwordx4 v0, s[0:1]
	s_add_i32 m0, s24, 0x16000
	v_mov_b32_e32 v143, v1
	global_load_lds_dwordx4 v138, s[0:1]
	v_readlane_b32 s0, v254, 9
	v_readlane_b32 s1, v254, 10
	s_add_u32 s0, s4, s0
	s_addc_u32 s1, s5, s1
	s_add_i32 s50, s24, 0x2000
	s_mov_b32 m0, s24
	s_add_u32 s2, s0, 0x80000
	global_load_lds_dwordx4 v142, s[0:1]
	s_mov_b32 m0, s50
	s_addc_u32 s3, s1, 0
	s_add_i32 s51, s24, 0x4000
	global_load_lds_dwordx4 v140, s[0:1]
	s_mov_b32 m0, s51
	s_add_i32 s52, s24, 0x6000
	global_load_lds_dwordx4 v142, s[2:3]
	s_mov_b32 m0, s52
	v_mov_b32_e32 v141, v1
	global_load_lds_dwordx4 v140, s[2:3]
	s_cmp_eq_u32 s36, 1
	v_lshl_add_u64 v[8:9], s[46:47], 0, v[0:1]
	v_lshl_add_u64 v[6:7], s[46:47], 0, v[138:139]
	v_lshl_add_u64 v[2:3], s[0:1], 0, v[142:143]
	s_cselect_b64 s[2:3], -1, 0
	s_cmp_lg_u32 s36, 1
	v_lshl_add_u64 v[4:5], s[0:1], 0, v[140:141]
	s_cbranch_scc1 .LBB0_1657
	s_barrier
